# chunked f32-MFMA scan: compute stage rescheduled (fillers in MFMA gaps, X-init overlapped with substitution, q-major update)
# baseline (speedup 1.0000x reference)
.Lmy_ck_mE:
	s_waitcnt lgkmcnt(0)
	s_barrier
	s_cmpk_ge_u32 s62, 0x100
	s_cbranch_scc1 .Lmy_ck_cE
	ds_read_b128 v[80:83], v225 offset:8448
	ds_read_b32 v84, v230
	ds_read_b32 v85, v230 offset:256
	ds_read_b32 v86, v230 offset:512
	ds_read_b32 v87, v230 offset:768
	ds_read_b128 v[88:91], v225
	ds_read_b128 v[92:95], v225 offset:1024
	ds_read_b128 v[96:99], v225 offset:2048
	ds_read_b128 v[100:103], v225 offset:3072
	ds_read_b32 v104, v227 offset:4
	ds_read_b32 v105, v227 offset:8
	ds_read_b32 v106, v227 offset:40
	ds_read_b32 v107, v227 offset:12
	ds_read_b32 v108, v227 offset:44
	ds_read_b32 v109, v227 offset:76
	ds_read_b32 v110, v228
	ds_read_b32 v111, v228 offset:32
	ds_read_b32 v112, v228 offset:64
	ds_read_b32 v113, v228 offset:96
	ds_read_b32 v114, v228 offset:4
	ds_read_b32 v115, v228 offset:36
	ds_read_b32 v116, v228 offset:68
	ds_read_b32 v117, v228 offset:100
	ds_read_b32 v118, v228 offset:8
	ds_read_b32 v119, v228 offset:40
	ds_read_b32 v120, v228 offset:72
	ds_read_b32 v121, v228 offset:104
	ds_read_b32 v122, v228 offset:12
	ds_read_b32 v123, v228 offset:44
	ds_read_b32 v124, v228 offset:76
	ds_read_b32 v125, v228 offset:108
	ds_read_b32 v126, v229 offset:4
	ds_read_b32 v127, v229 offset:8
	ds_read_b32 v128, v229 offset:40
	ds_read_b32 v129, v229 offset:12
	ds_read_b32 v130, v229 offset:44
	ds_read_b32 v131, v229 offset:76
	s_waitcnt lgkmcnt(15)
	v_cndmask_b32_e64 v76, 0, v84, s[98:99]
	v_cndmask_b32_e64 v77, 0, v85, s[98:99]
	v_cndmask_b32_e64 v78, 0, v86, s[98:99]
	v_cndmask_b32_e64 v79, 0, v87, s[98:99]
	v_mfma_f32_16x16x4_f32 v[240:243], v80, v76, 0
	v_mfma_f32_16x16x4_f32 v[240:243], v81, v77, v[240:243]
	v_mfma_f32_16x16x4_f32 v[240:243], v82, v78, v[240:243]
	v_mfma_f32_16x16x4_f32 v[240:243], v83, v79, v[240:243]
	v_mfma_f32_16x16x4_f32 v[240:243], v88, v208, v[240:243]
	ds_read_b128 v[184:187], v236 offset:4096
	ds_read_b128 v[188:191], v236 offset:5120
	v_mfma_f32_16x16x4_f32 v[244:247], v89, v209, 0
	ds_read_b128 v[192:195], v236 offset:6144
	ds_read_b128 v[196:199], v236 offset:7168
	v_mfma_f32_16x16x4_f32 v[240:243], v90, v210, v[240:243]
	ds_read_b128 v[132:135], v225 offset:18432
	ds_read_b32 v136, v230 offset:2048
	ds_read_b32 v137, v230 offset:2304
	v_mfma_f32_16x16x4_f32 v[244:247], v91, v211, v[244:247]
	ds_read_b32 v138, v230 offset:2560
	ds_read_b32 v139, v230 offset:2816
	ds_read_b128 v[140:143], v225 offset:9984
	v_mfma_f32_16x16x4_f32 v[240:243], v92, v212, v[240:243]
	ds_read_b128 v[144:147], v225 offset:11008
	ds_read_b128 v[148:151], v225 offset:12032
	ds_read_b128 v[152:155], v225 offset:13056
	v_mfma_f32_16x16x4_f32 v[244:247], v93, v213, v[244:247]
	ds_read_b32 v156, v227 offset:9988
	ds_read_b32 v157, v227 offset:9992
	ds_read_b32 v158, v227 offset:10024
	v_mfma_f32_16x16x4_f32 v[240:243], v94, v214, v[240:243]
	ds_read_b32 v159, v227 offset:9996
	ds_read_b32 v160, v227 offset:10028
	ds_read_b32 v161, v227 offset:10060
	v_mfma_f32_16x16x4_f32 v[244:247], v95, v215, v[244:247]
	ds_read_b32 v162, v228 offset:9984
	ds_read_b32 v163, v228 offset:10016
	ds_read_b32 v164, v228 offset:10048
	v_mfma_f32_16x16x4_f32 v[240:243], v96, v216, v[240:243]
	ds_read_b32 v165, v228 offset:10080
	ds_read_b32 v166, v228 offset:9988
	ds_read_b32 v167, v228 offset:10020
	v_mfma_f32_16x16x4_f32 v[244:247], v97, v217, v[244:247]
	ds_read_b32 v168, v228 offset:10052
	ds_read_b32 v169, v228 offset:10084
	ds_read_b32 v170, v228 offset:9992
	v_mfma_f32_16x16x4_f32 v[240:243], v98, v218, v[240:243]
	ds_read_b32 v171, v228 offset:10024
	ds_read_b32 v172, v228 offset:10056
	ds_read_b32 v173, v228 offset:10088
	v_mfma_f32_16x16x4_f32 v[244:247], v99, v219, v[244:247]
	ds_read_b32 v174, v228 offset:9996
	ds_read_b32 v175, v228 offset:10028
	ds_read_b32 v176, v228 offset:10060
	v_mfma_f32_16x16x4_f32 v[240:243], v100, v220, v[240:243]
	ds_read_b32 v177, v228 offset:10092
	ds_read_b32 v178, v229 offset:9988
	ds_read_b32 v179, v229 offset:9992
	v_mfma_f32_16x16x4_f32 v[244:247], v101, v221, v[244:247]
	ds_read_b32 v180, v229 offset:10024
	ds_read_b32 v181, v229 offset:9996
	ds_read_b32 v182, v229 offset:10028
	v_mfma_f32_16x16x4_f32 v[240:243], v102, v222, v[240:243]
	ds_read_b32 v183, v229 offset:10060
	v_mfma_f32_16x16x4_f32 v[244:247], v103, v223, v[244:247]
	s_nop 9
	v_add_f32_e32 v240, v240, v244
	v_add_f32_e32 v241, v241, v245
	v_add_f32_e32 v242, v242, v246
	v_add_f32_e32 v243, v243, v247
	v_fmac_f32_e32 v241, v104, v240
	v_fmac_f32_e32 v242, v105, v240
	v_fmac_f32_e32 v242, v106, v241
	v_fmac_f32_e32 v243, v107, v240
	v_fmac_f32_e32 v243, v108, v241
	v_fmac_f32_e32 v243, v109, v242
	ds_bpermute_b32 v204, v232, v240
	ds_bpermute_b32 v205, v232, v241
	ds_bpermute_b32 v206, v232, v242
	ds_bpermute_b32 v207, v232, v243
	ds_read_b128 v[88:91], v226
	ds_read_b128 v[92:95], v226 offset:64
	ds_read_b128 v[96:99], v226 offset:128
	ds_read_b128 v[100:103], v226 offset:192
	s_waitcnt lgkmcnt(15)
	v_cndmask_b32_e64 v76, 0, v136, s[98:99]
	v_cndmask_b32_e64 v77, 0, v137, s[98:99]
	v_cndmask_b32_e64 v78, 0, v138, s[98:99]
	v_cndmask_b32_e64 v79, 0, v139, s[98:99]
	v_mfma_f32_16x16x4_f32 v[72:75], v132, v76, 0
	s_waitcnt lgkmcnt(7)
	v_fmac_f32_e32 v240, v110, v204
	s_waitcnt lgkmcnt(6)
	v_fmac_f32_e32 v240, v111, v205
	s_waitcnt lgkmcnt(5)
	v_fmac_f32_e32 v240, v112, v206
	s_waitcnt lgkmcnt(4)
	v_fmac_f32_e32 v240, v113, v207
	v_fmac_f32_e32 v241, v114, v204
	v_fmac_f32_e32 v241, v115, v205
	v_mfma_f32_16x16x4_f32 v[72:75], v133, v77, v[72:75]
	v_fmac_f32_e32 v241, v116, v206
	v_fmac_f32_e32 v241, v117, v207
	v_fmac_f32_e32 v242, v118, v204
	v_fmac_f32_e32 v242, v119, v205
	v_fmac_f32_e32 v242, v120, v206
	v_fmac_f32_e32 v242, v121, v207
	v_mfma_f32_16x16x4_f32 v[72:75], v134, v78, v[72:75]
	v_fmac_f32_e32 v243, v122, v204
	v_fmac_f32_e32 v243, v123, v205
	v_fmac_f32_e32 v243, v124, v206
	v_fmac_f32_e32 v243, v125, v207
	v_mfma_f32_16x16x4_f32 v[72:75], v135, v79, v[72:75]
	v_fmac_f32_e32 v241, v126, v240
	v_fmac_f32_e32 v242, v127, v240
	v_fmac_f32_e32 v242, v128, v241
	v_fmac_f32_e32 v243, v129, v240
	v_fmac_f32_e32 v243, v130, v241
	v_fmac_f32_e32 v243, v131, v242
	v_cndmask_b32_e64 v200, v240, v84, s[98:99]
	v_cndmask_b32_e64 v201, v241, v85, s[98:99]
	v_cndmask_b32_e64 v202, v242, v86, s[98:99]
	v_cndmask_b32_e64 v203, v243, v87, s[98:99]
	v_cndmask_b32_e64 v252, v240, 0, s[98:99]
	v_cndmask_b32_e64 v253, v241, 0, s[98:99]
	v_cndmask_b32_e64 v254, v242, 0, s[98:99]
	v_cndmask_b32_e64 v255, v243, 0, s[98:99]
	v_mfma_f32_16x16x4_f32 v[208:211], v184, v200, v[208:211]
	v_mfma_f32_16x16x4_f32 v[212:215], v188, v200, v[212:215]
	v_mfma_f32_16x16x4_f32 v[216:219], v192, v200, v[216:219]
	v_mfma_f32_16x16x4_f32 v[220:223], v196, v200, v[220:223]
	v_mfma_f32_16x16x4_f32 v[208:211], v185, v201, v[208:211]
	v_mfma_f32_16x16x4_f32 v[212:215], v189, v201, v[212:215]
	v_mfma_f32_16x16x4_f32 v[216:219], v193, v201, v[216:219]
	v_mfma_f32_16x16x4_f32 v[220:223], v197, v201, v[220:223]
	v_mfma_f32_16x16x4_f32 v[208:211], v186, v202, v[208:211]
	v_mfma_f32_16x16x4_f32 v[212:215], v190, v202, v[212:215]
	v_mfma_f32_16x16x4_f32 v[216:219], v194, v202, v[216:219]
	v_mfma_f32_16x16x4_f32 v[220:223], v198, v202, v[220:223]
	v_mfma_f32_16x16x4_f32 v[208:211], v187, v203, v[208:211]
	v_mfma_f32_16x16x4_f32 v[212:215], v191, v203, v[212:215]
	v_mfma_f32_16x16x4_f32 v[216:219], v195, v203, v[216:219]
	v_mfma_f32_16x16x4_f32 v[220:223], v199, v203, v[220:223]
	v_mfma_f32_16x16x4_f32 v[248:251], v80, v252, v[240:243]
	v_mfma_f32_16x16x4_f32 v[248:251], v81, v253, v[248:251]
	v_mfma_f32_16x16x4_f32 v[248:251], v82, v254, v[248:251]
	v_mfma_f32_16x16x4_f32 v[248:251], v83, v255, v[248:251]
	s_waitcnt lgkmcnt(3)
	s_nop 2
	v_mul_f32_e32 v208, v208, v88
	v_mul_f32_e32 v209, v209, v89
	v_mul_f32_e32 v210, v210, v90
	v_mul_f32_e32 v211, v211, v91
	v_mfma_f32_16x16x4_f32 v[72:75], v140, v208, v[72:75]
	s_waitcnt lgkmcnt(2)
	v_mul_f32_e32 v212, v212, v92
	v_mul_f32_e32 v213, v213, v93
	v_mfma_f32_16x16x4_f32 v[244:247], v141, v209, 0
	v_mul_f32_e32 v214, v214, v94
	v_mul_f32_e32 v215, v215, v95
	v_mfma_f32_16x16x4_f32 v[72:75], v142, v210, v[72:75]
	s_waitcnt lgkmcnt(1)
	v_mul_f32_e32 v216, v216, v96
	v_mul_f32_e32 v217, v217, v97
	v_mfma_f32_16x16x4_f32 v[244:247], v143, v211, v[244:247]
	v_mul_f32_e32 v218, v218, v98
	v_mul_f32_e32 v219, v219, v99
	v_mfma_f32_16x16x4_f32 v[72:75], v144, v212, v[72:75]
	s_waitcnt lgkmcnt(0)
	v_mul_f32_e32 v220, v220, v100
	v_mul_f32_e32 v221, v221, v101
	v_mfma_f32_16x16x4_f32 v[244:247], v145, v213, v[244:247]
	v_mul_f32_e32 v222, v222, v102
	v_mul_f32_e32 v223, v223, v103
	v_mfma_f32_16x16x4_f32 v[72:75], v146, v214, v[72:75]
	s_mov_b64 exec, s[98:99]
	ds_write_b32 v231, v248
	ds_write_b32 v231, v249 offset:256
	ds_write_b32 v231, v250 offset:512
	ds_write_b32 v231, v251 offset:768
	s_mov_b64 exec, -1
	ds_read_b128 v[184:187], v236 offset:14080
	ds_read_b128 v[188:191], v236 offset:15104
	v_mfma_f32_16x16x4_f32 v[244:247], v147, v215, v[244:247]
	ds_read_b128 v[192:195], v236 offset:16128
	ds_read_b128 v[196:199], v236 offset:17152
	v_mfma_f32_16x16x4_f32 v[72:75], v148, v216, v[72:75]
	ds_read_b128 v[80:83], v225 offset:33280
	ds_read_b32 v84, v230 offset:4096
	ds_read_b32 v85, v230 offset:4352
	ds_read_b32 v86, v230 offset:4608
	ds_read_b32 v87, v230 offset:4864
	v_mfma_f32_16x16x4_f32 v[244:247], v149, v217, v[244:247]
	ds_read_b128 v[88:91], v225 offset:24832
	ds_read_b128 v[92:95], v225 offset:25856
	ds_read_b128 v[96:99], v225 offset:26880
	ds_read_b128 v[100:103], v225 offset:27904
	ds_read_b32 v104, v227 offset:24836
	v_mfma_f32_16x16x4_f32 v[72:75], v150, v218, v[72:75]
	ds_read_b32 v105, v227 offset:24840
	ds_read_b32 v106, v227 offset:24872
	ds_read_b32 v107, v227 offset:24844
	ds_read_b32 v108, v227 offset:24876
	ds_read_b32 v109, v227 offset:24908
	v_mfma_f32_16x16x4_f32 v[244:247], v151, v219, v[244:247]
	ds_read_b32 v110, v228 offset:24832
	ds_read_b32 v111, v228 offset:24864
	ds_read_b32 v112, v228 offset:24896
	ds_read_b32 v113, v228 offset:24928
	ds_read_b32 v114, v228 offset:24836
	v_mfma_f32_16x16x4_f32 v[72:75], v152, v220, v[72:75]
	ds_read_b32 v115, v228 offset:24868
	ds_read_b32 v116, v228 offset:24900
	ds_read_b32 v117, v228 offset:24932
	ds_read_b32 v118, v228 offset:24840
	ds_read_b32 v119, v228 offset:24872
	v_mfma_f32_16x16x4_f32 v[244:247], v153, v221, v[244:247]
	ds_read_b32 v120, v228 offset:24904
	ds_read_b32 v121, v228 offset:24936
	ds_read_b32 v122, v228 offset:24844
	ds_read_b32 v123, v228 offset:24876
	ds_read_b32 v124, v228 offset:24908
	v_mfma_f32_16x16x4_f32 v[72:75], v154, v222, v[72:75]
	ds_read_b32 v125, v228 offset:24940
	ds_read_b32 v126, v229 offset:24836
	ds_read_b32 v127, v229 offset:24840
	ds_read_b32 v128, v229 offset:24872
	ds_read_b32 v129, v229 offset:24844
	v_mfma_f32_16x16x4_f32 v[244:247], v155, v223, v[244:247]
	ds_read_b32 v130, v229 offset:24876
	ds_read_b32 v131, v229 offset:24908
	s_nop 7
	v_add_f32_e32 v72, v72, v244
	v_add_f32_e32 v73, v73, v245
	v_add_f32_e32 v74, v74, v246
	v_add_f32_e32 v75, v75, v247
	v_fmac_f32_e32 v73, v156, v72
	v_fmac_f32_e32 v74, v157, v72
	v_fmac_f32_e32 v74, v158, v73
	v_fmac_f32_e32 v75, v159, v72
	v_fmac_f32_e32 v75, v160, v73
	v_fmac_f32_e32 v75, v161, v74
	ds_bpermute_b32 v204, v232, v72
	ds_bpermute_b32 v205, v232, v73
	ds_bpermute_b32 v206, v232, v74
	ds_bpermute_b32 v207, v232, v75
	ds_read_b128 v[140:143], v226 offset:9984
	ds_read_b128 v[144:147], v226 offset:10048
	ds_read_b128 v[148:151], v226 offset:10112
	ds_read_b128 v[152:155], v226 offset:10176
	s_waitcnt lgkmcnt(15)
	v_cndmask_b32_e64 v76, 0, v84, s[98:99]
	v_cndmask_b32_e64 v77, 0, v85, s[98:99]
	v_cndmask_b32_e64 v78, 0, v86, s[98:99]
	v_cndmask_b32_e64 v79, 0, v87, s[98:99]
	v_mfma_f32_16x16x4_f32 v[240:243], v80, v76, 0
	s_waitcnt lgkmcnt(7)
	v_fmac_f32_e32 v72, v162, v204
	s_waitcnt lgkmcnt(6)
	v_fmac_f32_e32 v72, v163, v205
	s_waitcnt lgkmcnt(5)
	v_fmac_f32_e32 v72, v164, v206
	s_waitcnt lgkmcnt(4)
	v_fmac_f32_e32 v72, v165, v207
	v_fmac_f32_e32 v73, v166, v204
	v_fmac_f32_e32 v73, v167, v205
	v_mfma_f32_16x16x4_f32 v[240:243], v81, v77, v[240:243]
	v_fmac_f32_e32 v73, v168, v206
	v_fmac_f32_e32 v73, v169, v207
	v_fmac_f32_e32 v74, v170, v204
	v_fmac_f32_e32 v74, v171, v205
	v_fmac_f32_e32 v74, v172, v206
	v_fmac_f32_e32 v74, v173, v207
	v_mfma_f32_16x16x4_f32 v[240:243], v82, v78, v[240:243]
	v_fmac_f32_e32 v75, v174, v204
	v_fmac_f32_e32 v75, v175, v205
	v_fmac_f32_e32 v75, v176, v206
	v_fmac_f32_e32 v75, v177, v207
	v_mfma_f32_16x16x4_f32 v[240:243], v83, v79, v[240:243]
	v_fmac_f32_e32 v73, v178, v72
	v_fmac_f32_e32 v74, v179, v72
	v_fmac_f32_e32 v74, v180, v73
	v_fmac_f32_e32 v75, v181, v72
	v_fmac_f32_e32 v75, v182, v73
	v_fmac_f32_e32 v75, v183, v74
	v_cndmask_b32_e64 v200, v72, v136, s[98:99]
	v_cndmask_b32_e64 v201, v73, v137, s[98:99]
	v_cndmask_b32_e64 v202, v74, v138, s[98:99]
	v_cndmask_b32_e64 v203, v75, v139, s[98:99]
	v_cndmask_b32_e64 v252, v72, 0, s[98:99]
	v_cndmask_b32_e64 v253, v73, 0, s[98:99]
	v_cndmask_b32_e64 v254, v74, 0, s[98:99]
	v_cndmask_b32_e64 v255, v75, 0, s[98:99]
	v_mfma_f32_16x16x4_f32 v[208:211], v184, v200, v[208:211]
	v_mfma_f32_16x16x4_f32 v[212:215], v188, v200, v[212:215]
	v_mfma_f32_16x16x4_f32 v[216:219], v192, v200, v[216:219]
	v_mfma_f32_16x16x4_f32 v[220:223], v196, v200, v[220:223]
	v_mfma_f32_16x16x4_f32 v[208:211], v185, v201, v[208:211]
	v_mfma_f32_16x16x4_f32 v[212:215], v189, v201, v[212:215]
	v_mfma_f32_16x16x4_f32 v[216:219], v193, v201, v[216:219]
	v_mfma_f32_16x16x4_f32 v[220:223], v197, v201, v[220:223]
	v_mfma_f32_16x16x4_f32 v[208:211], v186, v202, v[208:211]
	v_mfma_f32_16x16x4_f32 v[212:215], v190, v202, v[212:215]
	v_mfma_f32_16x16x4_f32 v[216:219], v194, v202, v[216:219]
	v_mfma_f32_16x16x4_f32 v[220:223], v198, v202, v[220:223]
	v_mfma_f32_16x16x4_f32 v[208:211], v187, v203, v[208:211]
	v_mfma_f32_16x16x4_f32 v[212:215], v191, v203, v[212:215]
	v_mfma_f32_16x16x4_f32 v[216:219], v195, v203, v[216:219]
	v_mfma_f32_16x16x4_f32 v[220:223], v199, v203, v[220:223]
	v_mfma_f32_16x16x4_f32 v[248:251], v132, v252, v[72:75]
	v_mfma_f32_16x16x4_f32 v[248:251], v133, v253, v[248:251]
	v_mfma_f32_16x16x4_f32 v[248:251], v134, v254, v[248:251]
	v_mfma_f32_16x16x4_f32 v[248:251], v135, v255, v[248:251]
	s_waitcnt lgkmcnt(3)
	s_nop 2
	v_mul_f32_e32 v208, v208, v140
	v_mul_f32_e32 v209, v209, v141
	v_mul_f32_e32 v210, v210, v142
	v_mul_f32_e32 v211, v211, v143
	v_mfma_f32_16x16x4_f32 v[240:243], v88, v208, v[240:243]
	s_waitcnt lgkmcnt(2)
	v_mul_f32_e32 v212, v212, v144
	v_mul_f32_e32 v213, v213, v145
	v_mfma_f32_16x16x4_f32 v[244:247], v89, v209, 0
	v_mul_f32_e32 v214, v214, v146
	v_mul_f32_e32 v215, v215, v147
	v_mfma_f32_16x16x4_f32 v[240:243], v90, v210, v[240:243]
	s_waitcnt lgkmcnt(1)
	v_mul_f32_e32 v216, v216, v148
	v_mul_f32_e32 v217, v217, v149
	v_mfma_f32_16x16x4_f32 v[244:247], v91, v211, v[244:247]
	v_mul_f32_e32 v218, v218, v150
	v_mul_f32_e32 v219, v219, v151
	v_mfma_f32_16x16x4_f32 v[240:243], v92, v212, v[240:243]
	s_waitcnt lgkmcnt(0)
	v_mul_f32_e32 v220, v220, v152
	v_mul_f32_e32 v221, v221, v153
	v_mfma_f32_16x16x4_f32 v[244:247], v93, v213, v[244:247]
	v_mul_f32_e32 v222, v222, v154
	v_mul_f32_e32 v223, v223, v155
	v_mfma_f32_16x16x4_f32 v[240:243], v94, v214, v[240:243]
	s_mov_b64 exec, s[98:99]
	ds_write_b32 v231, v248 offset:2048
	ds_write_b32 v231, v249 offset:2304
	ds_write_b32 v231, v250 offset:2560
	ds_write_b32 v231, v251 offset:2816
	s_mov_b64 exec, -1
	ds_read_b128 v[184:187], v236 offset:28928
	ds_read_b128 v[188:191], v236 offset:29952
	v_mfma_f32_16x16x4_f32 v[244:247], v95, v215, v[244:247]
	ds_read_b128 v[192:195], v236 offset:30976
	ds_read_b128 v[196:199], v236 offset:32000
	v_mfma_f32_16x16x4_f32 v[240:243], v96, v216, v[240:243]
	ds_read_b128 v[132:135], v225 offset:43264
	ds_read_b32 v136, v230 offset:6144
	ds_read_b32 v137, v230 offset:6400
	ds_read_b32 v138, v230 offset:6656
	ds_read_b32 v139, v230 offset:6912
	v_mfma_f32_16x16x4_f32 v[244:247], v97, v217, v[244:247]
	ds_read_b128 v[140:143], v225 offset:34816
	ds_read_b128 v[144:147], v225 offset:35840
	ds_read_b128 v[148:151], v225 offset:36864
	ds_read_b128 v[152:155], v225 offset:37888
	ds_read_b32 v156, v227 offset:34820
	v_mfma_f32_16x16x4_f32 v[240:243], v98, v218, v[240:243]
	ds_read_b32 v157, v227 offset:34824
	ds_read_b32 v158, v227 offset:34856
	ds_read_b32 v159, v227 offset:34828
	ds_read_b32 v160, v227 offset:34860
	ds_read_b32 v161, v227 offset:34892
	v_mfma_f32_16x16x4_f32 v[244:247], v99, v219, v[244:247]
	ds_read_b32 v162, v228 offset:34816
	ds_read_b32 v163, v228 offset:34848
	ds_read_b32 v164, v228 offset:34880
	ds_read_b32 v165, v228 offset:34912
	ds_read_b32 v166, v228 offset:34820
	v_mfma_f32_16x16x4_f32 v[240:243], v100, v220, v[240:243]
	ds_read_b32 v167, v228 offset:34852
	ds_read_b32 v168, v228 offset:34884
	ds_read_b32 v169, v228 offset:34916
	ds_read_b32 v170, v228 offset:34824
	ds_read_b32 v171, v228 offset:34856
	v_mfma_f32_16x16x4_f32 v[244:247], v101, v221, v[244:247]
	ds_read_b32 v172, v228 offset:34888
	ds_read_b32 v173, v228 offset:34920
	ds_read_b32 v174, v228 offset:34828
	ds_read_b32 v175, v228 offset:34860
	ds_read_b32 v176, v228 offset:34892
	v_mfma_f32_16x16x4_f32 v[240:243], v102, v222, v[240:243]
	ds_read_b32 v177, v228 offset:34924
	ds_read_b32 v178, v229 offset:34820
	ds_read_b32 v179, v229 offset:34824
	ds_read_b32 v180, v229 offset:34856
	ds_read_b32 v181, v229 offset:34828
	v_mfma_f32_16x16x4_f32 v[244:247], v103, v223, v[244:247]
	ds_read_b32 v182, v229 offset:34860
	ds_read_b32 v183, v229 offset:34892
	s_nop 7
	v_add_f32_e32 v240, v240, v244
	v_add_f32_e32 v241, v241, v245
	v_add_f32_e32 v242, v242, v246
	v_add_f32_e32 v243, v243, v247
	v_fmac_f32_e32 v241, v104, v240
	v_fmac_f32_e32 v242, v105, v240
	v_fmac_f32_e32 v242, v106, v241
	v_fmac_f32_e32 v243, v107, v240
	v_fmac_f32_e32 v243, v108, v241
	v_fmac_f32_e32 v243, v109, v242
	ds_bpermute_b32 v204, v232, v240
	ds_bpermute_b32 v205, v232, v241
	ds_bpermute_b32 v206, v232, v242
	ds_bpermute_b32 v207, v232, v243
	ds_read_b128 v[88:91], v226 offset:24832
	ds_read_b128 v[92:95], v226 offset:24896
	ds_read_b128 v[96:99], v226 offset:24960
	ds_read_b128 v[100:103], v226 offset:25024
	s_waitcnt lgkmcnt(15)
	v_cndmask_b32_e64 v76, 0, v136, s[98:99]
	v_cndmask_b32_e64 v77, 0, v137, s[98:99]
	v_cndmask_b32_e64 v78, 0, v138, s[98:99]
	v_cndmask_b32_e64 v79, 0, v139, s[98:99]
	v_mfma_f32_16x16x4_f32 v[72:75], v132, v76, 0
	s_waitcnt lgkmcnt(7)
	v_fmac_f32_e32 v240, v110, v204
	s_waitcnt lgkmcnt(6)
	v_fmac_f32_e32 v240, v111, v205
	s_waitcnt lgkmcnt(5)
	v_fmac_f32_e32 v240, v112, v206
	s_waitcnt lgkmcnt(4)
	v_fmac_f32_e32 v240, v113, v207
	v_fmac_f32_e32 v241, v114, v204
	v_fmac_f32_e32 v241, v115, v205
	v_mfma_f32_16x16x4_f32 v[72:75], v133, v77, v[72:75]
	v_fmac_f32_e32 v241, v116, v206
	v_fmac_f32_e32 v241, v117, v207
	v_fmac_f32_e32 v242, v118, v204
	v_fmac_f32_e32 v242, v119, v205
	v_fmac_f32_e32 v242, v120, v206
	v_fmac_f32_e32 v242, v121, v207
	v_mfma_f32_16x16x4_f32 v[72:75], v134, v78, v[72:75]
	v_fmac_f32_e32 v243, v122, v204
	v_fmac_f32_e32 v243, v123, v205
	v_fmac_f32_e32 v243, v124, v206
	v_fmac_f32_e32 v243, v125, v207
	v_mfma_f32_16x16x4_f32 v[72:75], v135, v79, v[72:75]
	v_fmac_f32_e32 v241, v126, v240
	v_fmac_f32_e32 v242, v127, v240
	v_fmac_f32_e32 v242, v128, v241
	v_fmac_f32_e32 v243, v129, v240
	v_fmac_f32_e32 v243, v130, v241
	v_fmac_f32_e32 v243, v131, v242
	v_cndmask_b32_e64 v200, v240, v84, s[98:99]
	v_cndmask_b32_e64 v201, v241, v85, s[98:99]
	v_cndmask_b32_e64 v202, v242, v86, s[98:99]
	v_cndmask_b32_e64 v203, v243, v87, s[98:99]
	v_cndmask_b32_e64 v252, v240, 0, s[98:99]
	v_cndmask_b32_e64 v253, v241, 0, s[98:99]
	v_cndmask_b32_e64 v254, v242, 0, s[98:99]
	v_cndmask_b32_e64 v255, v243, 0, s[98:99]
	v_mfma_f32_16x16x4_f32 v[208:211], v184, v200, v[208:211]
	v_mfma_f32_16x16x4_f32 v[212:215], v188, v200, v[212:215]
	v_mfma_f32_16x16x4_f32 v[216:219], v192, v200, v[216:219]
	v_mfma_f32_16x16x4_f32 v[220:223], v196, v200, v[220:223]
	v_mfma_f32_16x16x4_f32 v[208:211], v185, v201, v[208:211]
	v_mfma_f32_16x16x4_f32 v[212:215], v189, v201, v[212:215]
	v_mfma_f32_16x16x4_f32 v[216:219], v193, v201, v[216:219]
	v_mfma_f32_16x16x4_f32 v[220:223], v197, v201, v[220:223]
	v_mfma_f32_16x16x4_f32 v[208:211], v186, v202, v[208:211]
	v_mfma_f32_16x16x4_f32 v[212:215], v190, v202, v[212:215]
	v_mfma_f32_16x16x4_f32 v[216:219], v194, v202, v[216:219]
	v_mfma_f32_16x16x4_f32 v[220:223], v198, v202, v[220:223]
	v_mfma_f32_16x16x4_f32 v[208:211], v187, v203, v[208:211]
	v_mfma_f32_16x16x4_f32 v[212:215], v191, v203, v[212:215]
	v_mfma_f32_16x16x4_f32 v[216:219], v195, v203, v[216:219]
	v_mfma_f32_16x16x4_f32 v[220:223], v199, v203, v[220:223]
	v_mfma_f32_16x16x4_f32 v[248:251], v80, v252, v[240:243]
	v_mfma_f32_16x16x4_f32 v[248:251], v81, v253, v[248:251]
	v_mfma_f32_16x16x4_f32 v[248:251], v82, v254, v[248:251]
	v_mfma_f32_16x16x4_f32 v[248:251], v83, v255, v[248:251]
	s_waitcnt lgkmcnt(3)
	s_nop 2
	v_mul_f32_e32 v208, v208, v88
	v_mul_f32_e32 v209, v209, v89
	v_mul_f32_e32 v210, v210, v90
	v_mul_f32_e32 v211, v211, v91
	v_mfma_f32_16x16x4_f32 v[72:75], v140, v208, v[72:75]
	s_waitcnt lgkmcnt(2)
	v_mul_f32_e32 v212, v212, v92
	v_mul_f32_e32 v213, v213, v93
	v_mfma_f32_16x16x4_f32 v[244:247], v141, v209, 0
	v_mul_f32_e32 v214, v214, v94
	v_mul_f32_e32 v215, v215, v95
	v_mfma_f32_16x16x4_f32 v[72:75], v142, v210, v[72:75]
	s_waitcnt lgkmcnt(1)
	v_mul_f32_e32 v216, v216, v96
	v_mul_f32_e32 v217, v217, v97
	v_mfma_f32_16x16x4_f32 v[244:247], v143, v211, v[244:247]
	v_mul_f32_e32 v218, v218, v98
	v_mul_f32_e32 v219, v219, v99
	v_mfma_f32_16x16x4_f32 v[72:75], v144, v212, v[72:75]
	s_waitcnt lgkmcnt(0)
	v_mul_f32_e32 v220, v220, v100
	v_mul_f32_e32 v221, v221, v101
	v_mfma_f32_16x16x4_f32 v[244:247], v145, v213, v[244:247]
	v_mul_f32_e32 v222, v222, v102
	v_mul_f32_e32 v223, v223, v103
	v_mfma_f32_16x16x4_f32 v[72:75], v146, v214, v[72:75]
	s_mov_b64 exec, s[98:99]
	ds_write_b32 v231, v248 offset:4096
	ds_write_b32 v231, v249 offset:4352
	ds_write_b32 v231, v250 offset:4608
	ds_write_b32 v231, v251 offset:4864
	s_mov_b64 exec, -1
	ds_read_b128 v[184:187], v236 offset:38912
	ds_read_b128 v[188:191], v236 offset:39936
	v_mfma_f32_16x16x4_f32 v[244:247], v147, v215, v[244:247]
	ds_read_b128 v[192:195], v236 offset:40960
	ds_read_b128 v[196:199], v236 offset:41984
	v_mfma_f32_16x16x4_f32 v[72:75], v148, v216, v[72:75]
	v_mfma_f32_16x16x4_f32 v[244:247], v149, v217, v[244:247]
	v_mfma_f32_16x16x4_f32 v[72:75], v150, v218, v[72:75]
	v_mfma_f32_16x16x4_f32 v[244:247], v151, v219, v[244:247]
	v_mfma_f32_16x16x4_f32 v[72:75], v152, v220, v[72:75]
	v_mfma_f32_16x16x4_f32 v[244:247], v153, v221, v[244:247]
	v_mfma_f32_16x16x4_f32 v[72:75], v154, v222, v[72:75]
	v_mfma_f32_16x16x4_f32 v[244:247], v155, v223, v[244:247]
	s_nop 9
	v_add_f32_e32 v72, v72, v244
	v_add_f32_e32 v73, v73, v245
	v_add_f32_e32 v74, v74, v246
	v_add_f32_e32 v75, v75, v247
	v_fmac_f32_e32 v73, v156, v72
	v_fmac_f32_e32 v74, v157, v72
	v_fmac_f32_e32 v74, v158, v73
	v_fmac_f32_e32 v75, v159, v72
	v_fmac_f32_e32 v75, v160, v73
	v_fmac_f32_e32 v75, v161, v74
	ds_bpermute_b32 v204, v232, v72
	ds_bpermute_b32 v205, v232, v73
	ds_bpermute_b32 v206, v232, v74
	ds_bpermute_b32 v207, v232, v75
	ds_read_b128 v[140:143], v226 offset:34816
	ds_read_b128 v[144:147], v226 offset:34880
	ds_read_b128 v[148:151], v226 offset:34944
	ds_read_b128 v[152:155], v226 offset:35008
	s_waitcnt lgkmcnt(7)
	v_fmac_f32_e32 v72, v162, v204
	s_waitcnt lgkmcnt(6)
	v_fmac_f32_e32 v72, v163, v205
	s_waitcnt lgkmcnt(5)
	v_fmac_f32_e32 v72, v164, v206
	s_waitcnt lgkmcnt(4)
	v_fmac_f32_e32 v72, v165, v207
	v_fmac_f32_e32 v73, v166, v204
	v_fmac_f32_e32 v73, v167, v205
	v_fmac_f32_e32 v73, v168, v206
	v_fmac_f32_e32 v73, v169, v207
	v_fmac_f32_e32 v74, v170, v204
	v_fmac_f32_e32 v74, v171, v205
	v_fmac_f32_e32 v74, v172, v206
	v_fmac_f32_e32 v74, v173, v207
	v_fmac_f32_e32 v75, v174, v204
	v_fmac_f32_e32 v75, v175, v205
	v_fmac_f32_e32 v75, v176, v206
	v_fmac_f32_e32 v75, v177, v207
	v_fmac_f32_e32 v73, v178, v72
	v_fmac_f32_e32 v74, v179, v72
	v_fmac_f32_e32 v74, v180, v73
	v_fmac_f32_e32 v75, v181, v72
	v_fmac_f32_e32 v75, v182, v73
	v_fmac_f32_e32 v75, v183, v74
	v_cndmask_b32_e64 v200, v72, v136, s[98:99]
	v_cndmask_b32_e64 v201, v73, v137, s[98:99]
	v_cndmask_b32_e64 v202, v74, v138, s[98:99]
	v_cndmask_b32_e64 v203, v75, v139, s[98:99]
	v_cndmask_b32_e64 v252, v72, 0, s[98:99]
	v_cndmask_b32_e64 v253, v73, 0, s[98:99]
	v_cndmask_b32_e64 v254, v74, 0, s[98:99]
	v_cndmask_b32_e64 v255, v75, 0, s[98:99]
	v_mfma_f32_16x16x4_f32 v[208:211], v184, v200, v[208:211]
	v_mfma_f32_16x16x4_f32 v[212:215], v188, v200, v[212:215]
	v_mfma_f32_16x16x4_f32 v[216:219], v192, v200, v[216:219]
	v_mfma_f32_16x16x4_f32 v[220:223], v196, v200, v[220:223]
	v_mfma_f32_16x16x4_f32 v[208:211], v185, v201, v[208:211]
	v_mfma_f32_16x16x4_f32 v[212:215], v189, v201, v[212:215]
	v_mfma_f32_16x16x4_f32 v[216:219], v193, v201, v[216:219]
	v_mfma_f32_16x16x4_f32 v[220:223], v197, v201, v[220:223]
	v_mfma_f32_16x16x4_f32 v[208:211], v186, v202, v[208:211]
	v_mfma_f32_16x16x4_f32 v[212:215], v190, v202, v[212:215]
	v_mfma_f32_16x16x4_f32 v[216:219], v194, v202, v[216:219]
	v_mfma_f32_16x16x4_f32 v[220:223], v198, v202, v[220:223]
	v_mfma_f32_16x16x4_f32 v[208:211], v187, v203, v[208:211]
	v_mfma_f32_16x16x4_f32 v[212:215], v191, v203, v[212:215]
	v_mfma_f32_16x16x4_f32 v[216:219], v195, v203, v[216:219]
	v_mfma_f32_16x16x4_f32 v[220:223], v199, v203, v[220:223]
	v_mfma_f32_16x16x4_f32 v[248:251], v132, v252, v[72:75]
	v_mfma_f32_16x16x4_f32 v[248:251], v133, v253, v[248:251]
	v_mfma_f32_16x16x4_f32 v[248:251], v134, v254, v[248:251]
	v_mfma_f32_16x16x4_f32 v[248:251], v135, v255, v[248:251]
	s_waitcnt lgkmcnt(3)
	s_nop 2
	v_mul_f32_e32 v208, v208, v140
	v_mul_f32_e32 v209, v209, v141
	v_mul_f32_e32 v210, v210, v142
	v_mul_f32_e32 v211, v211, v143
	s_waitcnt lgkmcnt(2)
	v_mul_f32_e32 v212, v212, v144
	v_mul_f32_e32 v213, v213, v145
	v_mul_f32_e32 v214, v214, v146
	v_mul_f32_e32 v215, v215, v147
	s_waitcnt lgkmcnt(1)
	v_mul_f32_e32 v216, v216, v148
	v_mul_f32_e32 v217, v217, v149
	v_mul_f32_e32 v218, v218, v150
	v_mul_f32_e32 v219, v219, v151
	s_waitcnt lgkmcnt(0)
	v_mul_f32_e32 v220, v220, v152
	v_mul_f32_e32 v221, v221, v153
	v_mul_f32_e32 v222, v222, v154
	v_mul_f32_e32 v223, v223, v155
	s_mov_b64 exec, s[98:99]
	ds_write_b32 v231, v248 offset:6144
	ds_write_b32 v231, v249 offset:6400
	ds_write_b32 v231, v250 offset:6656
	ds_write_b32 v231, v251 offset:6912
	s_mov_b64 exec, -1
